# P2b rebalanced: all FoX segment-table items run on the scan half so the memory-attention half is shorter
# baseline (speedup 1.0000x reference)
; #define LAS __attribute__((address_space(3)))
; __global__ void __launch_bounds__(NTHR, 2) fwd_mega(Params P) {
;     ...
;           else { int tp = tid; asm volatile("" : "+v"(tp));
;               for (int it = bx - hg; it < 128; it += G - hg) { asm volatile("" : "+v"(tp)); mem_attn(P, l, lds, it, tp); }
;               for (int it = 128 + bx - hg; it < 256; it += G - hg) { asm volatile("" : "+v"(tp)); fox_seg(P, l, it, (LAS float*)lds, tp); } } }
.LBB0_417:
	v_readlane_b32 s0, v254, 1
	v_readlane_b32 s1, v254, 2
	s_andn2_b64 vcc, exec, s[0:1]
	s_branch .LBB0_446
	s_lshl_b32 s12, s73, 3
	v_readlane_b32 s13, v255, 2
	v_readlane_b32 s14, v255, 1
	s_branch .LBB0_420

; #define LAS __attribute__((address_space(3)))
; __global__ void __launch_bounds__(NTHR, 2) fwd_mega(Params P) {
;     ...
;           if (bx < hg) { int tp = tid; asm volatile("" : "+v"(tp)); gla_scan(P, tp, bx, hg);
;               for (int it = bx; it < 128; it += hg) { asm volatile("" : "+v"(tp)); fox_seg(P, l, it, (LAS float*)lds, tp); } }
.LBB0_455:
	s_or_b64 exec, exec, s[4:5]
	v_readlane_b32 s0, v255, 6
	s_add_i32 s14, s14, s0
	v_readlane_b32 s0, v255, 3
	s_add_i32 s13, s13, s0
	s_cmpk_gt_i32 s14, 0xff
	s_cbranch_scc1 .LBB0_482
